# attention: K/V LDS-DMA for tile t+3 issued after the QK MFMAs instead of at step top
# speedup vs baseline: 1.0084x; 1.0016x over previous
.LBB0_740:
	s_add_i32 s26, s48, 3
	s_cmp_ge_u32 s26, s46
	s_cselect_b64 s[2:3], -1, 0
.LBB0_743:
	s_sub_i32 s26, s49, 63
	s_cmp_le_i32 s26, s47
	s_cselect_b64 s[28:29], -1, 0
	s_cmp_gt_i32 s26, s47
	s_cbranch_scc1 .LBB0_756
	s_and_b32 s26, s48, 3
	s_mulk_i32 s26, 0x5800
	s_add_i32 s26, s26, 0
	v_add3_u32 v159, s26, v147, v146
	v_add3_u32 v232, s26, v156, v146
	ds_read_b128 v[168:171], v159
	ds_read_b128 v[192:195], v159 offset:6656
	ds_read_b128 v[172:175], v159 offset:32
	ds_read_b128 v[196:199], v159 offset:6688
	ds_read_b128 v[176:179], v159 offset:64
	ds_read_b128 v[200:203], v159 offset:6720
	ds_read_b128 v[180:183], v159 offset:96
	ds_read_b128 v[204:207], v159 offset:6752
	ds_read_b128 v[184:187], v159 offset:128
	ds_read_b128 v[208:211], v159 offset:6784
	ds_read_b128 v[188:191], v159 offset:160
	ds_read_b128 v[212:215], v159 offset:6816
	s_waitcnt lgkmcnt(10)
	v_mfma_f32_32x32x16_bf16 v[32:47], v[168:171], v[96:99], v[216:231]
	v_mfma_f32_32x32x16_bf16 v[48:63], v[192:195], v[96:99], v[216:231]
	ds_read_b128 v[108:111], v232 offset:13312
	ds_read_b128 v[124:127], v232 offset:17920
	s_waitcnt lgkmcnt(10)
	v_mfma_f32_32x32x16_bf16 v[32:47], v[172:175], v[80:83], v[32:47]
	v_mfma_f32_32x32x16_bf16 v[48:63], v[196:199], v[80:83], v[48:63]
	ds_read_b128 v[104:107], v232 offset:13344
	ds_read_b128 v[120:123], v232 offset:17952
	s_waitcnt lgkmcnt(10)
	v_mfma_f32_32x32x16_bf16 v[32:47], v[176:179], v[84:87], v[32:47]
	v_mfma_f32_32x32x16_bf16 v[48:63], v[200:203], v[84:87], v[48:63]
	ds_read_b128 v[112:115], v232 offset:13376
	ds_read_b128 v[132:135], v232 offset:17984
	s_waitcnt lgkmcnt(10)
	v_mfma_f32_32x32x16_bf16 v[32:47], v[180:183], v[88:91], v[32:47]
	v_mfma_f32_32x32x16_bf16 v[48:63], v[204:207], v[88:91], v[48:63]
	ds_read_b128 v[116:119], v232 offset:13408
	ds_read_b128 v[128:131], v232 offset:18016
	s_waitcnt lgkmcnt(10)
	v_mfma_f32_32x32x16_bf16 v[32:47], v[184:187], v[92:95], v[32:47]
	v_mfma_f32_32x32x16_bf16 v[48:63], v[208:211], v[92:95], v[48:63]
	s_waitcnt lgkmcnt(8)
	v_mfma_f32_32x32x16_bf16 v[32:47], v[188:191], v[100:103], v[32:47]
	v_mfma_f32_32x32x16_bf16 v[48:63], v[212:215], v[100:103], v[48:63]
	s_mov_b64 s[26:27], -1
	s_and_b64 vcc, exec, s[2:3]
	s_cbranch_vccnz .LBB0_757

.LBB0_746:
	s_add_i32 s26, s48, 3
	s_and_b32 s26, s26, 3
	s_mulk_i32 s26, 0x5800
	s_add_i32 s26, s45, s26
	s_mov_b32 m0, s26
	s_andn2_b64 vcc, exec, s[24:25]
	global_load_lds_dwordx4 v[152:153], off
	s_add_i32 m0, s26, 0x2000
	s_nop 0
	global_load_lds_dwordx4 v[150:151], off
	s_cbranch_vccnz .Ldma_done
	s_add_i32 m0, s26, 0x4000
	s_nop 0
	global_load_lds_dwordx4 v[148:149], off
